# v44
# speedup vs baseline: 1.0004x; 1.0004x over previous
.LBB0_192:
	s_and_b32 s4, s4, 0x3fffffc0
	v_and_b32_e32 v49, 63, v171
	s_lshl_b32 s4, s4, 2
	s_lshr_b32 s23, s23, 6
	s_add_i32 s4, s4, 0
	v_lshlrev_b32_e32 v50, 8, v160
	v_and_b32_e32 v51, 0x70, v171
	v_lshlrev_b32_e32 v52, 4, v49
	s_add_i32 s23, s23, 4
	s_add_i32 s26, s4, 0x10000
	v_bitop3_b32 v51, v184, v50, v51 bitop3:0xde
	v_lshlrev_b32_e32 v50, 3, v49
	v_and_b32_e32 v52, 0xc0, v52
	v_lshlrev_b32_e32 v53, 1, v49
	v_and_or_b32 v52, v50, 24, v52
	v_and_b32_e32 v53, 32, v53
	v_and_b32_e32 v50, 0x100, v50
	s_cmp_lg_u32 0, -1
	v_or3_b32 v50, v52, v53, v50
	s_cselect_b32 s4, 0, 0
	v_add_u32_e32 v173, s4, v50
	v_max_f32_e32 v50, v17, v17
	v_max_f32_e32 v52, v16, v16
	v_max_f32_e32 v50, v52, v50
	v_max3_f32 v50, v50, v18, v19
	v_max3_f32 v50, v50, v20, v21
	v_max3_f32 v50, v50, v22, v23
	v_max3_f32 v50, v50, v24, v25
	v_max3_f32 v50, v50, v26, v27
	v_max3_f32 v50, v50, v28, v29
	v_max3_f32 v50, v50, v30, v31
	v_max3_f32 v50, v50, v0, v1
	v_max3_f32 v50, v50, v2, v3
	v_max3_f32 v50, v50, v4, v5
	v_max3_f32 v50, v50, v6, v7
	v_max3_f32 v50, v50, v8, v9
	v_max3_f32 v50, v50, v10, v11
	v_max3_f32 v50, v50, v12, v13
	v_max3_f32 v50, v50, v14, v15
	v_mov_b32_e32 v52, v50
	s_nop 1
	v_permlane32_swap_b32_e32 v50, v52
	v_max_f32_e32 v52, v52, v52
	v_max_f32_e32 v50, v50, v50
	v_max_f32_e32 v50, v50, v52
	v_add_f32_e32 v52, 0x7149f2ca, v50
	v_mul_f32_e32 v52, 0x3db504f3, v52
	v_max_f32_e32 v50, 0xf149f2ca, v50
	v_cmp_ge_f32_e32 vcc, s87, v52
	v_sub_f32_e32 v52, 0xf149f2ca, v50
	s_add_i32 s24, s19, 0xffffe01f
	v_mul_f32_e32 v52, 0x3e0293ee, v52
	v_exp_f32_e32 v52, v52
	s_cmp_eq_u64 vcc, exec
	s_cselect_b64 vcc, -1, 0
	v_cndmask_b32_e32 v186, v50, v203, vcc
	v_mul_f32_e32 v50, 0xbe0293ee, v186
	v_cndmask_b32_e64 v183, v52, 1.0, vcc
	v_mov_b32_e32 v52, v50
	v_fmamk_f32 v16, v16, 0x3e0293ee, v50
	v_fmamk_f32 v17, v17, 0x3e0293ee, v50
	v_fmamk_f32 v18, v18, 0x3e0293ee, v50
	v_fmamk_f32 v19, v19, 0x3e0293ee, v50
	v_fmamk_f32 v20, v20, 0x3e0293ee, v50
	v_fmamk_f32 v21, v21, 0x3e0293ee, v50
	v_fmamk_f32 v22, v22, 0x3e0293ee, v50
	v_fmamk_f32 v23, v23, 0x3e0293ee, v50
	v_fmamk_f32 v24, v24, 0x3e0293ee, v50
	v_fmamk_f32 v25, v25, 0x3e0293ee, v50
	v_fmamk_f32 v26, v26, 0x3e0293ee, v50
	v_fmamk_f32 v27, v27, 0x3e0293ee, v50
	v_fmamk_f32 v28, v28, 0x3e0293ee, v50
	v_fmamk_f32 v29, v29, 0x3e0293ee, v50
	v_fmamk_f32 v30, v30, 0x3e0293ee, v50
	v_fmac_f32_e32 v52, 0x3e0293ee, v31
	v_lshl_add_u64 v[166:167], s[0:1], 0, v[184:185]
	s_add_i32 s0, s19, 0xffffdf45
	v_pk_fma_f32 v[156:157], v[0:1], s[90:91], v[50:51] op_sel_hi:[1,0,0]
	v_exp_f32_e32 v216, v16
	v_exp_f32_e32 v219, v17
	v_exp_f32_e32 v213, v18
	v_exp_f32_e32 v217, v19
	v_exp_f32_e32 v212, v20
	v_exp_f32_e32 v214, v21
	v_exp_f32_e32 v210, v22
	v_exp_f32_e32 v211, v23
	v_exp_f32_e32 v207, v24
	v_exp_f32_e32 v209, v25
	v_exp_f32_e32 v206, v26
	v_exp_f32_e32 v208, v27
	v_exp_f32_e32 v195, v28
	v_exp_f32_e32 v197, v29
	v_exp_f32_e32 v194, v30
	v_exp_f32_e32 v196, v52
	v_add_u32_e32 v0, s0, v172
	s_waitcnt vmcnt(0)
	v_add_u32_e32 v176, 0, v51
	v_cmp_gt_u32_e64 s[4:5], 32, v49
	v_lshl_add_u32 v174, v48, 2, s26
	v_sub_u32_e32 v188, v0, v48
	v_mov_b32_e32 v48, v185
	v_mov_b32_e32 v49, v185
	v_pk_fma_f32 v[146:147], v[14:15], s[90:91], v[50:51] op_sel_hi:[1,0,0]
	v_pk_fma_f32 v[152:153], v[12:13], s[90:91], v[50:51] op_sel_hi:[1,0,0]
	v_pk_fma_f32 v[158:159], v[10:11], s[90:91], v[50:51] op_sel_hi:[1,0,0]
	v_pk_fma_f32 v[144:145], v[8:9], s[90:91], v[50:51] op_sel_hi:[1,0,0]
	v_pk_fma_f32 v[148:149], v[6:7], s[90:91], v[50:51] op_sel_hi:[1,0,0]
	v_pk_fma_f32 v[150:151], v[4:5], s[90:91], v[50:51] op_sel_hi:[1,0,0]
	v_pk_fma_f32 v[154:155], v[2:3], s[90:91], v[50:51] op_sel_hi:[1,0,0]
	s_waitcnt vmcnt(3)
	ds_write_b128 v181, v[32:35] offset:16384
	s_waitcnt vmcnt(2)
	ds_write_b128 v182, v[36:39] offset:16384
	s_waitcnt vmcnt(1)
	ds_write_b128 v176, v[40:43] offset:49152
	s_waitcnt vmcnt(0)
	ds_write_b128 v176, v[44:47] offset:57344
	v_mov_b32_e32 v50, v185
	v_mov_b32_e32 v51, v185
	v_mov_b32_e32 v52, v185
	v_mov_b32_e32 v53, v185
	v_mov_b32_e32 v54, v185
	v_mov_b32_e32 v55, v185
	v_mov_b32_e32 v56, v185
	v_mov_b32_e32 v57, v185
	v_mov_b32_e32 v58, v185
	v_mov_b32_e32 v59, v185
	v_mov_b32_e32 v60, v185
	v_mov_b32_e32 v61, v185
	v_mov_b32_e32 v62, v185
	v_mov_b32_e32 v63, v185
	v_mov_b64_e32 v[32:33], v[48:49]
	v_mov_b64_e32 v[16:17], v[48:49]
	v_mov_b64_e32 v[0:1], v[48:49]
	s_mov_b32 s25, 2
	v_lshl_add_u64 v[168:169], s[2:3], 0, v[184:185]
	v_lshl_add_u32 v175, v172, 2, s26
	v_mov_b32_e32 v177, 0
	s_movk_i32 s26, 0x7f
	v_mov_b64_e32 v[34:35], v[50:51]
	v_mov_b64_e32 v[36:37], v[52:53]
	v_mov_b64_e32 v[38:39], v[54:55]
	v_mov_b64_e32 v[40:41], v[56:57]
	v_mov_b64_e32 v[42:43], v[58:59]
	v_mov_b64_e32 v[44:45], v[60:61]
	v_mov_b64_e32 v[46:47], v[62:63]
	v_mov_b64_e32 v[18:19], v[50:51]
	v_mov_b64_e32 v[20:21], v[52:53]
	v_mov_b64_e32 v[22:23], v[54:55]
	v_mov_b64_e32 v[24:25], v[56:57]
	v_mov_b64_e32 v[26:27], v[58:59]
	v_mov_b64_e32 v[28:29], v[60:61]
	v_mov_b64_e32 v[30:31], v[62:63]
	v_mov_b64_e32 v[2:3], v[50:51]
	v_mov_b64_e32 v[4:5], v[52:53]
	v_mov_b64_e32 v[6:7], v[54:55]
	v_mov_b64_e32 v[8:9], v[56:57]
	v_mov_b64_e32 v[10:11], v[58:59]
	v_mov_b64_e32 v[12:13], v[60:61]
	v_mov_b64_e32 v[14:15], v[62:63]
	s_waitcnt lgkmcnt(0)
	s_barrier
	v_readfirstlane_b32 s27, v187
	s_nop 3
	s_cmpk_lt_u32 s27, 0x100
	s_cbranch_scc0 .Lprio_skip
	s_setprio 1
.Lprio_skip:
.LBB0_193:
	ds_read_b128 v[64:67], v180 offset:49152
	ds_read_b128 v[68:71], v180 offset:57344
	ds_read_b128 v[128:131], v179 offset:49152
	s_waitcnt vmcnt(2)
	ds_read_b128 v[132:135], v179 offset:57344
	ds_read_b128 v[248:251], v165 offset:49152
	ds_read_b128 v[252:255], v165 offset:57344
	s_waitcnt vmcnt(1)
	v_exp_f32_e32 v136, v144
	v_add_f32_e32 v144, 0, v216
	s_waitcnt lgkmcnt(5)
	v_mfma_f32_32x32x16_bf16 v[80:95], v[64:67], v[124:127], 0
	v_add_f32_e32 v144, v219, v144
	v_add_f32_e32 v144, v213, v144
	v_add_f32_e32 v144, v217, v144
	v_add_f32_e32 v144, v212, v144
	v_add_f32_e32 v144, v214, v144
	v_add_f32_e32 v144, v210, v144
	v_add_f32_e32 v144, v211, v144
	s_waitcnt lgkmcnt(4)
	v_mfma_f32_32x32x16_bf16 v[64:79], v[68:71], v[124:127], 0
	v_add_f32_e32 v144, v207, v144
	v_add_f32_e32 v144, v209, v144
	v_add_f32_e32 v144, v206, v144
	v_add_f32_e32 v144, v208, v144
	v_add_f32_e32 v144, v195, v144
	v_add_f32_e32 v144, v197, v144
	v_add_f32_e32 v144, v194, v144
	s_waitcnt lgkmcnt(3)
	v_mfma_f32_32x32x16_bf16 v[80:95], v[128:131], v[120:123], v[80:95]
	v_add_f32_e32 v144, v196, v144
	v_exp_f32_e32 v137, v145
	v_exp_f32_e32 v138, v158
	v_exp_f32_e32 v139, v159
	s_waitcnt vmcnt(0)
	v_exp_f32_e32 v140, v152
	v_exp_f32_e32 v141, v153
	v_exp_f32_e32 v142, v146
	s_waitcnt lgkmcnt(2)
	v_mfma_f32_32x32x16_bf16 v[64:79], v[132:135], v[120:123], v[64:79]
	ds_read_b128 v[128:131], v163 offset:49152
	ds_read_b128 v[132:135], v163 offset:57344
	v_exp_f32_e32 v143, v147
	s_sub_i32 s0, s26, 63
	s_waitcnt lgkmcnt(3)
	v_mfma_f32_32x32x16_bf16 v[80:95], v[248:251], v[116:119], v[80:95]
	s_waitcnt lgkmcnt(2)
	v_mfma_f32_32x32x16_bf16 v[64:79], v[252:255], v[116:119], v[64:79]
	ds_read_b128 v[248:251], v180 offset:49280
	ds_read_b128 v[252:255], v180 offset:57472
	s_waitcnt lgkmcnt(3)
	v_mfma_f32_32x32x16_bf16 v[80:95], v[128:131], v[112:115], v[80:95]
	s_waitcnt lgkmcnt(2)
	v_mfma_f32_32x32x16_bf16 v[64:79], v[132:135], v[112:115], v[64:79]
	ds_read_b128 v[128:131], v179 offset:49280
	ds_read_b128 v[132:135], v179 offset:57472
	s_waitcnt lgkmcnt(3)
	v_mfma_f32_32x32x16_bf16 v[80:95], v[248:251], v[108:111], v[80:95]
	s_waitcnt lgkmcnt(2)
	v_mfma_f32_32x32x16_bf16 v[64:79], v[252:255], v[108:111], v[64:79]
	ds_read_b128 v[248:251], v165 offset:49280
	ds_read_b128 v[252:255], v165 offset:57472
	s_waitcnt lgkmcnt(3)
	v_mfma_f32_32x32x16_bf16 v[80:95], v[128:131], v[104:107], v[80:95]
	s_waitcnt lgkmcnt(2)
	v_mfma_f32_32x32x16_bf16 v[64:79], v[132:135], v[104:107], v[64:79]
	ds_read_b128 v[128:131], v163 offset:49280
	ds_read_b128 v[132:135], v163 offset:57472
	s_waitcnt lgkmcnt(3)
	v_mfma_f32_32x32x16_bf16 v[80:95], v[248:251], v[100:103], v[80:95]
	s_waitcnt lgkmcnt(2)
	v_mfma_f32_32x32x16_bf16 v[64:79], v[252:255], v[100:103], v[64:79]
	s_waitcnt lgkmcnt(1)
	v_mfma_f32_32x32x16_bf16 v[80:95], v[128:131], v[96:99], v[80:95]
	v_exp_f32_e32 v128, v156
	v_exp_f32_e32 v129, v157
	v_exp_f32_e32 v130, v154
	v_exp_f32_e32 v131, v155
	v_add_f32_e32 v144, v128, v144
	v_add_f32_e32 v144, v129, v144
	v_add_f32_e32 v144, v130, v144
	s_waitcnt lgkmcnt(0)
	v_mfma_f32_32x32x16_bf16 v[64:79], v[132:135], v[96:99], v[64:79]
	v_exp_f32_e32 v132, v150
	v_exp_f32_e32 v133, v151
	v_exp_f32_e32 v134, v148
	v_exp_f32_e32 v135, v149
	v_add_f32_e32 v144, v131, v144
	v_add_f32_e32 v144, v132, v144
	v_add_f32_e32 v144, v133, v144
	v_add_f32_e32 v144, v134, v144
	v_add_f32_e32 v144, v135, v144
	v_add_f32_e32 v144, v136, v144
	v_add_f32_e32 v144, v137, v144
	v_add_f32_e32 v144, v138, v144
	v_add_f32_e32 v144, v139, v144
	v_add_f32_e32 v144, v140, v144
	v_add_f32_e32 v144, v141, v144
	v_add_f32_e32 v144, v142, v144
	v_add_f32_e32 v190, v143, v144
	v_mov_b32_e32 v191, v190
	s_nop 1
	v_permlane32_swap_b32_e32 v190, v191
	s_nop 0
	v_cvt_pk_bf16_f32 v144, v216, v219
	s_nop 0
	v_cvt_pk_bf16_f32 v145, v213, v217
	s_nop 0
	v_cvt_pk_bf16_f32 v146, v212, v214
	s_nop 0
	v_cvt_pk_bf16_f32 v147, v210, v211
	s_nop 0
	v_cvt_pk_bf16_f32 v148, v207, v209
	s_nop 0
	v_cvt_pk_bf16_f32 v149, v206, v208
	s_nop 0
	v_cvt_pk_bf16_f32 v150, v195, v197
	s_nop 0
	v_cvt_pk_bf16_f32 v151, v194, v196
	s_nop 0
	v_cvt_pk_bf16_f32 v152, v128, v129
	s_nop 0
	v_cvt_pk_bf16_f32 v153, v130, v131
	s_nop 0
	v_cvt_pk_bf16_f32 v154, v132, v133
	s_nop 0
	v_cvt_pk_bf16_f32 v155, v134, v135
	s_nop 0
	v_cvt_pk_bf16_f32 v156, v136, v137
	s_nop 0
	v_cvt_pk_bf16_f32 v157, v138, v139
	s_nop 0
	v_cvt_pk_bf16_f32 v158, v140, v141
	s_nop 0
	v_cvt_pk_bf16_f32 v159, v142, v143
	s_nop 0
	v_permlane32_swap_b32_e32 v144, v146
	v_permlane32_swap_b32_e32 v145, v147
	v_permlane32_swap_b32_e32 v148, v150
	v_permlane32_swap_b32_e32 v149, v151
	v_permlane32_swap_b32_e32 v152, v154
	v_permlane32_swap_b32_e32 v153, v155
	v_permlane32_swap_b32_e32 v156, v158
	v_permlane32_swap_b32_e32 v157, v159
	v_add_u32_e32 v192, s26, v160
	v_add_u32_e32 v128, 1, v192
	v_add_u32_e32 v130, 33, v192
	v_ashrrev_i32_e32 v129, 31, v128
	v_ashrrev_i32_e32 v131, 31, v130
	v_lshlrev_b64 v[136:137], 8, v[128:129]
	v_lshlrev_b64 v[138:139], 8, v[130:131]
	v_lshl_add_u64 v[128:129], v[166:167], 0, v[136:137]
	v_lshl_add_u64 v[132:133], v[166:167], 0, v[138:139]
	v_lshl_add_u64 v[136:137], v[168:169], 0, v[136:137]
	v_lshl_add_u64 v[140:141], v[168:169], 0, v[138:139]
	global_load_dwordx4 v[128:131], v[128:129], off
	s_nop 0
	global_load_dwordx4 v[132:135], v[132:133], off
	s_nop 0
	global_load_dwordx4 v[136:139], v[136:137], off
	s_nop 0
	global_load_dwordx4 v[140:143], v[140:141], off
	ds_read_b64_tr_b16 v[194:195], v173 offset:0
	ds_read_b64_tr_b16 v[196:197], v173 offset:0x800
	ds_read_b64_tr_b16 v[206:207], v173 offset:0x1000
	ds_read_b64_tr_b16 v[208:209], v173 offset:0x1800
	ds_read_b64_tr_b16 v[210:211], v173 offset:0x2000
	ds_read_b64_tr_b16 v[212:213], v173 offset:0x2800
	ds_read_b64_tr_b16 v[214:215], v173 offset:0x3000
	ds_read_b64_tr_b16 v[216:217], v173 offset:0x3800
	s_waitcnt lgkmcnt(0)
	s_nop 0
	v_mfma_f32_32x32x16_bf16 v[48:63], v[144:147], v[194:197], v[48:63]
	ds_read_b64_tr_b16 v[194:195], v173 offset:0x200
	ds_read_b64_tr_b16 v[196:197], v173 offset:0xa00
	v_mfma_f32_32x32x16_bf16 v[48:63], v[148:151], v[206:209], v[48:63]
	ds_read_b64_tr_b16 v[206:207], v173 offset:0x1200
	ds_read_b64_tr_b16 v[208:209], v173 offset:0x1a00
	v_mfma_f32_32x32x16_bf16 v[48:63], v[152:155], v[210:213], v[48:63]
	ds_read_b64_tr_b16 v[210:211], v173 offset:0x2200
	ds_read_b64_tr_b16 v[212:213], v173 offset:0x2a00
	v_mfma_f32_32x32x16_bf16 v[48:63], v[156:159], v[214:217], v[48:63]
	ds_read_b64_tr_b16 v[214:215], v173 offset:0x3200
	ds_read_b64_tr_b16 v[216:217], v173 offset:0x3a00
	s_waitcnt lgkmcnt(0)
	v_mfma_f32_32x32x16_bf16 v[32:47], v[144:147], v[194:197], v[32:47]
	ds_read_b64_tr_b16 v[194:195], v173 offset:0x400
	ds_read_b64_tr_b16 v[196:197], v173 offset:0xc00
	v_mfma_f32_32x32x16_bf16 v[32:47], v[148:151], v[206:209], v[32:47]
	ds_read_b64_tr_b16 v[206:207], v173 offset:0x1400
	ds_read_b64_tr_b16 v[208:209], v173 offset:0x1c00
	v_mfma_f32_32x32x16_bf16 v[32:47], v[152:155], v[210:213], v[32:47]
	ds_read_b64_tr_b16 v[210:211], v173 offset:0x2400
	ds_read_b64_tr_b16 v[212:213], v173 offset:0x2c00
	v_mfma_f32_32x32x16_bf16 v[32:47], v[156:159], v[214:217], v[32:47]
	ds_read_b64_tr_b16 v[214:215], v173 offset:0x3400
	ds_read_b64_tr_b16 v[216:217], v173 offset:0x3c00
	s_waitcnt lgkmcnt(0)
	v_mfma_f32_32x32x16_bf16 v[16:31], v[144:147], v[194:197], v[16:31]
	ds_read_b64_tr_b16 v[194:195], v173 offset:0x600
	ds_read_b64_tr_b16 v[196:197], v173 offset:0xe00
	v_mfma_f32_32x32x16_bf16 v[16:31], v[148:151], v[206:209], v[16:31]
	ds_read_b64_tr_b16 v[206:207], v173 offset:0x1600
	ds_read_b64_tr_b16 v[208:209], v173 offset:0x1e00
	v_mfma_f32_32x32x16_bf16 v[16:31], v[152:155], v[210:213], v[16:31]
	ds_read_b64_tr_b16 v[210:211], v173 offset:0x2600
	ds_read_b64_tr_b16 v[212:213], v173 offset:0x2e00
	v_mfma_f32_32x32x16_bf16 v[16:31], v[156:159], v[214:217], v[16:31]
	ds_read_b64_tr_b16 v[214:215], v173 offset:0x3600
	ds_read_b64_tr_b16 v[216:217], v173 offset:0x3e00
	s_waitcnt lgkmcnt(0)
	v_mfma_f32_32x32x16_bf16 v[0:15], v[144:147], v[194:197], v[0:15]
	s_cmp_le_i32 s26, s19
	s_cselect_b64 s[2:3], -1, 0
	s_cmp_gt_i32 s0, s24
	s_cselect_b64 s[0:1], -1, 0
	s_and_b64 s[0:1], s[2:3], s[0:1]
	s_and_b64 vcc, exec, s[0:1]
	v_mfma_f32_32x32x16_bf16 v[0:15], v[148:151], v[206:209], v[0:15]
	v_mfma_f32_32x32x16_bf16 v[0:15], v[152:155], v[210:213], v[0:15]
	v_mfma_f32_32x32x16_bf16 v[0:15], v[156:159], v[214:217], v[0:15]
	s_waitcnt vmcnt(0)
	ds_write_b128 v176, v[136:139] offset:32768
	ds_write_b128 v176, v[140:143] offset:40960
	s_cbranch_vccnz .LBB0_195
	v_add_u32_e32 v144, 0x207b, v188
	v_cmp_gt_u32_e32 vcc, s73, v144
	v_add_u32_e32 v144, 0x5b, v188
	s_nop 0
	v_cndmask_b32_e32 v80, v202, v80, vcc
	v_cmp_lt_u32_e32 vcc, s95, v144
	v_add_u32_e32 v144, 0x7a, v188
	s_nop 0
	v_cndmask_b32_e32 v64, v202, v64, vcc
	v_cmp_lt_u32_e32 vcc, s95, v144
	v_add_u32_e32 v144, 0x5a, v188
	s_nop 0
	v_cndmask_b32_e32 v81, v202, v81, vcc
	v_cmp_lt_u32_e32 vcc, s95, v144
	v_add_u32_e32 v144, 0x79, v188
	s_nop 0
	v_cndmask_b32_e32 v65, v202, v65, vcc
	v_cmp_lt_u32_e32 vcc, s95, v144
	v_add_u32_e32 v144, 0x59, v188
	s_nop 0
	v_cndmask_b32_e32 v82, v202, v82, vcc
	v_cmp_lt_u32_e32 vcc, s95, v144
	v_add_u32_e32 v144, 0x78, v188
	s_nop 0
	v_cndmask_b32_e32 v66, v202, v66, vcc
	v_cmp_lt_u32_e32 vcc, s95, v144
	v_add_u32_e32 v144, 0x58, v188
	s_nop 0
	v_cndmask_b32_e32 v83, v202, v83, vcc
	v_cmp_lt_u32_e32 vcc, s95, v144
	v_add_u32_e32 v144, 0x73, v188
	s_nop 0
	v_cndmask_b32_e32 v67, v202, v67, vcc
	v_cmp_lt_u32_e32 vcc, s95, v144
	v_add_u32_e32 v144, 0x53, v188
	s_nop 0
	v_cndmask_b32_e32 v84, v202, v84, vcc
	v_cmp_lt_u32_e32 vcc, s95, v144
	v_add_u32_e32 v144, 0x72, v188
	s_nop 0
	v_cndmask_b32_e32 v68, v202, v68, vcc
	v_cmp_lt_u32_e32 vcc, s95, v144
	v_add_u32_e32 v144, 0x52, v188
	s_nop 0
	v_cndmask_b32_e32 v85, v202, v85, vcc
	v_cmp_lt_u32_e32 vcc, s95, v144
	v_add_u32_e32 v144, 0x71, v188
	s_nop 0
	v_cndmask_b32_e32 v69, v202, v69, vcc
	v_cmp_lt_u32_e32 vcc, s95, v144
	v_add_u32_e32 v144, 0x51, v188
	s_nop 0
	v_cndmask_b32_e32 v86, v202, v86, vcc
	v_cmp_lt_u32_e32 vcc, s95, v144
	v_add_u32_e32 v144, 0x70, v188
	s_nop 0
	v_cndmask_b32_e32 v70, v202, v70, vcc
	v_cmp_lt_u32_e32 vcc, s95, v144
	v_add_u32_e32 v144, 0x50, v188
	s_nop 0
	v_cndmask_b32_e32 v87, v202, v87, vcc
	v_cmp_lt_u32_e32 vcc, s95, v144
	v_add_u32_e32 v144, 0x6b, v188
	s_nop 0
	v_cndmask_b32_e32 v71, v202, v71, vcc
	v_cmp_lt_u32_e32 vcc, s95, v144
	v_add_u32_e32 v144, 0x4b, v188
	s_nop 0
	v_cndmask_b32_e32 v88, v202, v88, vcc
	v_cmp_lt_u32_e32 vcc, s95, v144
	v_add_u32_e32 v144, 0x6a, v188
	s_nop 0
	v_cndmask_b32_e32 v72, v202, v72, vcc
	v_cmp_lt_u32_e32 vcc, s95, v144
	v_add_u32_e32 v144, 0x4a, v188
	s_nop 0
	v_cndmask_b32_e32 v89, v202, v89, vcc
	v_cmp_lt_u32_e32 vcc, s95, v144
	v_add_u32_e32 v144, 0x69, v188
	s_nop 0
	v_cndmask_b32_e32 v73, v202, v73, vcc
	v_cmp_lt_u32_e32 vcc, s95, v144
	v_add_u32_e32 v144, 0x49, v188
	s_nop 0
	v_cndmask_b32_e32 v90, v202, v90, vcc
	v_cmp_lt_u32_e32 vcc, s95, v144
	v_add_u32_e32 v144, 0x68, v188
	s_nop 0
	v_cndmask_b32_e32 v74, v202, v74, vcc
	v_cmp_lt_u32_e32 vcc, s95, v144
	v_add_u32_e32 v144, 0x48, v188
	s_nop 0
	v_cndmask_b32_e32 v91, v202, v91, vcc
	v_cmp_lt_u32_e32 vcc, s95, v144
	v_add_u32_e32 v144, 0x63, v188
	s_nop 0
	v_cndmask_b32_e32 v75, v202, v75, vcc
	v_cmp_lt_u32_e32 vcc, s95, v144
	v_add_u32_e32 v144, 0x43, v188
	s_nop 0
	v_cndmask_b32_e32 v92, v202, v92, vcc
	v_cmp_lt_u32_e32 vcc, s95, v144
	v_add_u32_e32 v144, 0x62, v188
	s_nop 0
	v_cndmask_b32_e32 v76, v202, v76, vcc
	v_cmp_lt_u32_e32 vcc, s95, v144
	v_add_u32_e32 v144, 0x42, v188
	s_nop 0
	v_cndmask_b32_e32 v93, v202, v93, vcc
	v_cmp_lt_u32_e32 vcc, s95, v144
	v_add_u32_e32 v144, 0x61, v188
	s_nop 0
	v_cndmask_b32_e32 v77, v202, v77, vcc
	v_cmp_lt_u32_e32 vcc, s95, v144
	v_add_u32_e32 v144, 0x41, v188
	s_nop 0
	v_cndmask_b32_e32 v94, v202, v94, vcc
	v_cmp_lt_u32_e32 vcc, s95, v144
	v_add_u32_e32 v144, 0x60, v188
	s_nop 0
	v_cndmask_b32_e32 v78, v202, v78, vcc
	v_cmp_lt_u32_e32 vcc, s95, v144
	v_add_u32_e32 v144, 64, v188
	s_nop 0
	v_cndmask_b32_e32 v95, v202, v95, vcc
	v_cmp_lt_u32_e32 vcc, s95, v144
	s_nop 1
	v_cndmask_b32_e32 v79, v202, v79, vcc

.LBB0_211:
	s_setprio 0
	ds_read_b128 v[64:67], v180 offset:49152
	ds_read_b128 v[68:71], v180 offset:57344
	s_waitcnt lgkmcnt(1)
	v_mfma_f32_32x32x16_bf16 v[80:95], v[64:67], v[124:127], 0
	s_waitcnt lgkmcnt(0)
	v_mfma_f32_32x32x16_bf16 v[64:79], v[68:71], v[124:127], 0
	ds_read_b128 v[124:127], v179 offset:49152
	ds_read_b128 v[128:131], v179 offset:57344
	s_waitcnt lgkmcnt(1)
	v_mfma_f32_32x32x16_bf16 v[80:95], v[124:127], v[120:123], v[80:95]
	s_waitcnt lgkmcnt(0)
	v_mfma_f32_32x32x16_bf16 v[64:79], v[128:131], v[120:123], v[64:79]
	ds_read_b128 v[120:123], v165 offset:49152
	ds_read_b128 v[124:127], v165 offset:57344
	s_waitcnt lgkmcnt(1)
	v_mfma_f32_32x32x16_bf16 v[80:95], v[120:123], v[116:119], v[80:95]
	s_waitcnt lgkmcnt(0)
	v_mfma_f32_32x32x16_bf16 v[64:79], v[124:127], v[116:119], v[64:79]
	ds_read_b128 v[116:119], v163 offset:49152
	ds_read_b128 v[120:123], v163 offset:57344
	s_waitcnt lgkmcnt(1)
	v_mfma_f32_32x32x16_bf16 v[80:95], v[116:119], v[112:115], v[80:95]
	s_waitcnt lgkmcnt(0)
	v_mfma_f32_32x32x16_bf16 v[64:79], v[120:123], v[112:115], v[64:79]
	ds_read_b128 v[112:115], v180 offset:49280
	ds_read_b128 v[116:119], v180 offset:57472
	s_waitcnt lgkmcnt(1)
	v_mfma_f32_32x32x16_bf16 v[80:95], v[112:115], v[108:111], v[80:95]
	s_waitcnt lgkmcnt(0)
	v_mfma_f32_32x32x16_bf16 v[64:79], v[116:119], v[108:111], v[64:79]
	ds_read_b128 v[108:111], v179 offset:49280
	ds_read_b128 v[112:115], v179 offset:57472
	s_waitcnt lgkmcnt(1)
	v_mfma_f32_32x32x16_bf16 v[80:95], v[108:111], v[104:107], v[80:95]
	s_waitcnt lgkmcnt(0)
	v_mfma_f32_32x32x16_bf16 v[64:79], v[112:115], v[104:107], v[64:79]
	ds_read_b128 v[104:107], v165 offset:49280
	ds_read_b128 v[108:111], v165 offset:57472
	s_waitcnt lgkmcnt(1)
	v_mfma_f32_32x32x16_bf16 v[80:95], v[104:107], v[100:103], v[80:95]
	s_waitcnt lgkmcnt(0)
	v_mfma_f32_32x32x16_bf16 v[64:79], v[108:111], v[100:103], v[64:79]
	ds_read_b128 v[100:103], v163 offset:49280
	ds_read_b128 v[104:107], v163 offset:57472
	s_waitcnt lgkmcnt(1)
	v_mfma_f32_32x32x16_bf16 v[80:95], v[100:103], v[96:99], v[80:95]
	s_waitcnt lgkmcnt(0)
	v_mfma_f32_32x32x16_bf16 v[64:79], v[104:107], v[96:99], v[64:79]
	v_lshlrev_b64 v[96:97], 8, v[160:161]
	v_ashrrev_i32_e32 v163, 31, v162
	v_lshl_add_u64 v[98:99], s[8:9], 0, v[96:97]
	v_lshlrev_b64 v[100:101], 8, v[162:163]
	v_lshl_add_u64 v[98:99], v[98:99], 0, v[184:185]
	v_lshl_add_u64 v[102:103], s[8:9], 0, v[100:101]
	v_lshl_add_u64 v[96:97], s[12:13], 0, v[96:97]
	v_lshl_add_u64 v[102:103], v[102:103], 0, v[184:185]
	global_load_dwordx4 v[128:131], v[98:99], off
	global_load_dwordx4 v[132:135], v[102:103], off
	v_lshl_add_u64 v[96:97], v[96:97], 0, v[184:185]
	v_lshl_add_u64 v[98:99], s[12:13], 0, v[100:101]
	v_lshl_add_u64 v[98:99], v[98:99], 0, v[184:185]
	global_load_dwordx4 v[136:139], v[96:97], off
	global_load_dwordx4 v[140:143], v[98:99], off
	v_or_b32_e32 v96, s18, v172
	v_ashrrev_i32_e32 v97, 31, v96
	v_lshlrev_b64 v[96:97], 8, v[96:97]
	v_lshl_add_u64 v[96:97], s[6:7], 0, v[96:97]
	v_mov_b32_e32 v165, v185
	v_lshl_add_u64 v[96:97], v[96:97], 0, v[164:165]
	global_load_dwordx4 v[124:127], v[96:97], off
	global_load_dwordx4 v[120:123], v[96:97], off offset:32
	global_load_dwordx4 v[116:119], v[96:97], off offset:64
	global_load_dwordx4 v[112:115], v[96:97], off offset:96
	global_load_dwordx4 v[108:111], v[96:97], off offset:128
	global_load_dwordx4 v[104:107], v[96:97], off offset:160
	global_load_dwordx4 v[100:103], v[96:97], off offset:192
	s_nop 0
	global_load_dwordx4 v[96:99], v[96:97], off offset:224
	v_exp_f32_e32 v165, v144
	v_add_f32_e32 v144, 0, v216
	v_add_f32_e32 v144, v219, v144
	v_add_f32_e32 v144, v213, v144
	v_add_f32_e32 v144, v217, v144
	v_add_f32_e32 v144, v212, v144
	v_add_f32_e32 v144, v214, v144
	v_add_f32_e32 v144, v210, v144
	v_add_f32_e32 v144, v211, v144
	v_add_f32_e32 v144, v207, v144
	v_add_f32_e32 v144, v209, v144
	v_add_f32_e32 v144, v206, v144
	v_add_f32_e32 v144, v208, v144
	v_exp_f32_e32 v156, v156
	v_add_f32_e32 v144, v195, v144
	v_exp_f32_e32 v157, v157
	v_add_f32_e32 v144, v197, v144
	v_exp_f32_e32 v160, v154
	v_add_f32_e32 v144, v194, v144
	v_exp_f32_e32 v155, v155
	v_add_f32_e32 v144, v196, v144
	v_exp_f32_e32 v161, v150
	v_add_f32_e32 v144, v156, v144
	v_exp_f32_e32 v162, v151
	v_add_f32_e32 v144, v157, v144
	v_exp_f32_e32 v163, v148
	v_add_f32_e32 v144, v160, v144
	v_exp_f32_e32 v164, v149
	v_add_f32_e32 v144, v155, v144
	v_add_f32_e32 v144, v161, v144
	v_exp_f32_e32 v166, v145
	v_add_f32_e32 v144, v162, v144
	v_exp_f32_e32 v167, v158
	v_add_f32_e32 v144, v163, v144
	v_exp_f32_e32 v159, v159
	v_add_f32_e32 v144, v164, v144
	v_exp_f32_e32 v168, v152
	v_add_f32_e32 v144, v165, v144
	v_exp_f32_e32 v169, v153
	v_add_f32_e32 v144, v166, v144
	v_exp_f32_e32 v179, v146
	v_add_f32_e32 v144, v167, v144
	v_exp_f32_e32 v180, v147
	v_add_f32_e32 v144, v159, v144
	v_add_f32_e32 v144, v168, v144
	v_add_f32_e32 v144, v169, v144
	v_add_f32_e32 v144, v179, v144
	v_add_f32_e32 v144, v180, v144
	v_mov_b32_e32 v145, v144
	s_nop 1
	v_permlane32_swap_b32_e32 v144, v145
	s_nop 0
	v_cvt_pk_bf16_f32 v146, v216, v219
	s_nop 0
	v_cvt_pk_bf16_f32 v147, v213, v217
	s_nop 0
	v_cvt_pk_bf16_f32 v148, v212, v214
	s_nop 0
	v_cvt_pk_bf16_f32 v149, v210, v211
	s_nop 0
	v_cvt_pk_bf16_f32 v150, v207, v209
	s_nop 0
	v_cvt_pk_bf16_f32 v151, v206, v208
	s_nop 0
	v_cvt_pk_bf16_f32 v152, v195, v197
	s_nop 0
	v_cvt_pk_bf16_f32 v153, v194, v196
	s_nop 0
	v_cvt_pk_bf16_f32 v154, v156, v157
	s_nop 0
	v_cvt_pk_bf16_f32 v155, v160, v155
	s_nop 0
	v_cvt_pk_bf16_f32 v156, v161, v162
	s_nop 0
	v_cvt_pk_bf16_f32 v157, v163, v164
	s_nop 0
	v_cvt_pk_bf16_f32 v158, v165, v166
	s_nop 0
	v_cvt_pk_bf16_f32 v159, v167, v159
	s_nop 0
	v_cvt_pk_bf16_f32 v160, v168, v169
	s_nop 0
	v_cvt_pk_bf16_f32 v161, v179, v180
	s_nop 0
	v_permlane32_swap_b32_e32 v146, v148
	v_permlane32_swap_b32_e32 v147, v149
	v_permlane32_swap_b32_e32 v150, v152
	v_permlane32_swap_b32_e32 v151, v153
	v_permlane32_swap_b32_e32 v154, v156
	v_permlane32_swap_b32_e32 v155, v157
	v_permlane32_swap_b32_e32 v158, v160
	v_permlane32_swap_b32_e32 v159, v161
	ds_read_b64_tr_b16 v[162:163], v173 offset:0
	ds_read_b64_tr_b16 v[164:165], v173 offset:0x800
	ds_read_b64_tr_b16 v[166:167], v173 offset:0x1000
	ds_read_b64_tr_b16 v[168:169], v173 offset:0x1800
	ds_read_b64_tr_b16 v[180:181], v173 offset:0x2000
	ds_read_b64_tr_b16 v[182:183], v173 offset:0x2800
	ds_read_b64_tr_b16 v[194:195], v173 offset:0x3000
	ds_read_b64_tr_b16 v[196:197], v173 offset:0x3800
	s_waitcnt lgkmcnt(0)
	s_nop 0
	v_mfma_f32_32x32x16_bf16 v[48:63], v[146:149], v[162:165], v[48:63]
	ds_read_b64_tr_b16 v[162:163], v173 offset:0x200
	ds_read_b64_tr_b16 v[164:165], v173 offset:0xa00
	v_mfma_f32_32x32x16_bf16 v[48:63], v[150:153], v[166:169], v[48:63]
	ds_read_b64_tr_b16 v[166:167], v173 offset:0x1200
	ds_read_b64_tr_b16 v[168:169], v173 offset:0x1a00
	v_mfma_f32_32x32x16_bf16 v[48:63], v[154:157], v[180:183], v[48:63]
	ds_read_b64_tr_b16 v[180:181], v173 offset:0x2200
	ds_read_b64_tr_b16 v[182:183], v173 offset:0x2a00
	v_mfma_f32_32x32x16_bf16 v[48:63], v[158:161], v[194:197], v[48:63]
	ds_read_b64_tr_b16 v[194:195], v173 offset:0x3200
	ds_read_b64_tr_b16 v[196:197], v173 offset:0x3a00
	s_waitcnt lgkmcnt(0)
	v_mfma_f32_32x32x16_bf16 v[32:47], v[146:149], v[162:165], v[32:47]
	ds_read_b64_tr_b16 v[162:163], v173 offset:0x400
	ds_read_b64_tr_b16 v[164:165], v173 offset:0xc00
	v_mfma_f32_32x32x16_bf16 v[32:47], v[150:153], v[166:169], v[32:47]
	ds_read_b64_tr_b16 v[166:167], v173 offset:0x1400
	ds_read_b64_tr_b16 v[168:169], v173 offset:0x1c00
	v_mfma_f32_32x32x16_bf16 v[32:47], v[154:157], v[180:183], v[32:47]
	ds_read_b64_tr_b16 v[180:181], v173 offset:0x2400
	ds_read_b64_tr_b16 v[182:183], v173 offset:0x2c00
	v_mfma_f32_32x32x16_bf16 v[32:47], v[158:161], v[194:197], v[32:47]
	ds_read_b64_tr_b16 v[194:195], v173 offset:0x3400
	ds_read_b64_tr_b16 v[196:197], v173 offset:0x3c00
	s_waitcnt lgkmcnt(0)
	v_mfma_f32_32x32x16_bf16 v[16:31], v[146:149], v[162:165], v[16:31]
	ds_read_b64_tr_b16 v[162:163], v173 offset:0x600
	ds_read_b64_tr_b16 v[164:165], v173 offset:0xe00
	v_mfma_f32_32x32x16_bf16 v[16:31], v[150:153], v[166:169], v[16:31]
	ds_read_b64_tr_b16 v[166:167], v173 offset:0x1600
	ds_read_b64_tr_b16 v[168:169], v173 offset:0x1e00
	v_mfma_f32_32x32x16_bf16 v[16:31], v[154:157], v[180:183], v[16:31]
	ds_read_b64_tr_b16 v[180:181], v173 offset:0x2600
	ds_read_b64_tr_b16 v[182:183], v173 offset:0x2e00
	v_mfma_f32_32x32x16_bf16 v[16:31], v[158:161], v[194:197], v[16:31]
	ds_read_b64_tr_b16 v[194:195], v173 offset:0x3600
	ds_read_b64_tr_b16 v[196:197], v173 offset:0x3e00
	s_waitcnt lgkmcnt(0)
	v_mfma_f32_32x32x16_bf16 v[0:15], v[146:149], v[162:165], v[0:15]
	s_lshl_b32 s1, s23, 6
	s_sub_i32 s0, s1, 64
	s_add_i32 s1, s1, -1
	s_cmp_le_i32 s1, s19
	s_cselect_b64 s[2:3], -1, 0
	s_cmp_gt_i32 s0, s24
	s_cselect_b64 s[24:25], -1, 0
	v_mfma_f32_32x32x16_bf16 v[0:15], v[150:153], v[166:169], v[0:15]
	s_and_b64 s[2:3], s[2:3], s[24:25]
	s_and_b64 vcc, exec, s[2:3]
	v_mfma_f32_32x32x16_bf16 v[0:15], v[154:157], v[180:183], v[0:15]
	v_mfma_f32_32x32x16_bf16 v[0:15], v[158:161], v[194:197], v[0:15]
	s_cbranch_vccnz .LBB0_213
	v_subrev_u32_e32 v146, s0, v178
	v_cmp_gt_u32_e32 vcc, s73, v146
	v_add_u32_e32 v147, 0xffffdfe0, v146
	s_nop 0
	v_cndmask_b32_e32 v80, v202, v80, vcc
	v_cmp_lt_u32_e32 vcc, s95, v147
	v_add_u32_e32 v147, 0xffffdfff, v146
	s_nop 0
	v_cndmask_b32_e32 v64, v202, v64, vcc
	v_cmp_lt_u32_e32 vcc, s95, v147
	v_add_u32_e32 v147, 0xffffdfdf, v146
	s_nop 0
	v_cndmask_b32_e32 v81, v202, v81, vcc
	v_cmp_lt_u32_e32 vcc, s95, v147
	v_add_u32_e32 v147, 0xffffdffe, v146
	s_nop 0
	v_cndmask_b32_e32 v65, v202, v65, vcc
	v_cmp_lt_u32_e32 vcc, s95, v147
	v_add_u32_e32 v147, 0xffffdfde, v146
	s_nop 0
	v_cndmask_b32_e32 v82, v202, v82, vcc
	v_cmp_lt_u32_e32 vcc, s95, v147
	v_add_u32_e32 v147, 0xffffdffd, v146
	s_nop 0
	v_cndmask_b32_e32 v66, v202, v66, vcc
	v_cmp_lt_u32_e32 vcc, s95, v147
	v_add_u32_e32 v147, 0xffffdfdd, v146
	s_nop 0
	v_cndmask_b32_e32 v83, v202, v83, vcc
	v_cmp_lt_u32_e32 vcc, s95, v147
	v_add_u32_e32 v147, 0xffffdff8, v146
	s_nop 0
	v_cndmask_b32_e32 v67, v202, v67, vcc
	v_cmp_lt_u32_e32 vcc, s95, v147
	v_add_u32_e32 v147, 0xffffdfd8, v146
	s_nop 0
	v_cndmask_b32_e32 v84, v202, v84, vcc
	v_cmp_lt_u32_e32 vcc, s95, v147
	v_add_u32_e32 v147, 0xffffdff7, v146
	s_nop 0
	v_cndmask_b32_e32 v68, v202, v68, vcc
	v_cmp_lt_u32_e32 vcc, s95, v147
	v_add_u32_e32 v147, 0xffffdfd7, v146
	s_nop 0
	v_cndmask_b32_e32 v85, v202, v85, vcc
	v_cmp_lt_u32_e32 vcc, s95, v147
	v_add_u32_e32 v147, 0xffffdff6, v146
	s_nop 0
	v_cndmask_b32_e32 v69, v202, v69, vcc
	v_cmp_lt_u32_e32 vcc, s95, v147
	v_add_u32_e32 v147, 0xffffdfd6, v146
	s_nop 0
	v_cndmask_b32_e32 v86, v202, v86, vcc
	v_cmp_lt_u32_e32 vcc, s95, v147
	v_add_u32_e32 v147, 0xffffdff5, v146
	s_nop 0
	v_cndmask_b32_e32 v70, v202, v70, vcc
	v_cmp_lt_u32_e32 vcc, s95, v147
	v_add_u32_e32 v147, 0xffffdfd5, v146
	s_nop 0
	v_cndmask_b32_e32 v87, v202, v87, vcc
	v_cmp_lt_u32_e32 vcc, s95, v147
	v_add_u32_e32 v147, 0xffffdff0, v146
	s_nop 0
	v_cndmask_b32_e32 v71, v202, v71, vcc
	v_cmp_lt_u32_e32 vcc, s95, v147
	v_add_u32_e32 v147, 0xffffdfd0, v146
	s_nop 0
	v_cndmask_b32_e32 v88, v202, v88, vcc
	v_cmp_lt_u32_e32 vcc, s95, v147
	v_add_u32_e32 v147, 0xffffdfef, v146
	s_nop 0
	v_cndmask_b32_e32 v72, v202, v72, vcc
	v_cmp_lt_u32_e32 vcc, s95, v147
	v_add_u32_e32 v147, 0xffffdfcf, v146
	s_nop 0
	v_cndmask_b32_e32 v89, v202, v89, vcc
	v_cmp_lt_u32_e32 vcc, s95, v147
	v_add_u32_e32 v147, 0xffffdfee, v146
	s_nop 0
	v_cndmask_b32_e32 v73, v202, v73, vcc
	v_cmp_lt_u32_e32 vcc, s95, v147
	v_add_u32_e32 v147, 0xffffdfce, v146
	s_nop 0
	v_cndmask_b32_e32 v90, v202, v90, vcc
	v_cmp_lt_u32_e32 vcc, s95, v147
	v_add_u32_e32 v147, 0xffffdfed, v146
	s_nop 0
	v_cndmask_b32_e32 v74, v202, v74, vcc
	v_cmp_lt_u32_e32 vcc, s95, v147
	v_add_u32_e32 v147, 0xffffdfcd, v146
	s_nop 0
	v_cndmask_b32_e32 v91, v202, v91, vcc
	v_cmp_lt_u32_e32 vcc, s95, v147
	v_add_u32_e32 v147, 0xffffdfe8, v146
	s_nop 0
	v_cndmask_b32_e32 v75, v202, v75, vcc
	v_cmp_lt_u32_e32 vcc, s95, v147
	v_add_u32_e32 v147, 0xffffdfc8, v146
	s_nop 0
	v_cndmask_b32_e32 v92, v202, v92, vcc
	v_cmp_lt_u32_e32 vcc, s95, v147
	v_add_u32_e32 v147, 0xffffdfe7, v146
	s_nop 0
	v_cndmask_b32_e32 v76, v202, v76, vcc
	v_cmp_lt_u32_e32 vcc, s95, v147
	v_add_u32_e32 v147, 0xffffdfc7, v146
	s_nop 0
	v_cndmask_b32_e32 v93, v202, v93, vcc
	v_cmp_lt_u32_e32 vcc, s95, v147
	v_add_u32_e32 v147, 0xffffdfe6, v146
	s_nop 0
	v_cndmask_b32_e32 v77, v202, v77, vcc
	v_cmp_lt_u32_e32 vcc, s95, v147
	v_add_u32_e32 v147, 0xffffdfc6, v146
	s_nop 0
	v_cndmask_b32_e32 v94, v202, v94, vcc
	v_cmp_lt_u32_e32 vcc, s95, v147
	v_add_u32_e32 v147, 0xffffdfe5, v146
	v_add_u32_e32 v146, 0xffffdfc5, v146
	v_cndmask_b32_e32 v78, v202, v78, vcc
	v_cmp_lt_u32_e32 vcc, s95, v147
	s_nop 1
	v_cndmask_b32_e32 v95, v202, v95, vcc
	v_cmp_lt_u32_e32 vcc, s95, v146
	s_nop 1
	v_cndmask_b32_e32 v79, v202, v79, vcc
